# gather: upper-half workgroups start about half a token later (de-phases the two workgroups of a CU so load bursts and conversion bursts interleave)
# baseline (speedup 1.0000x reference)
; DEV int opaque_tid() { int t = (int)threadIdx.x; asm volatile("" : "+v"(t)); return t; }
; __device__ void peer_gather_phase(const Params& P, int l, bool do_store) {
;   const int lane = opaque_tid() & 63, w = opaque_tid() >> 6;
;   const unsigned char* U = P.U8 + (size_t)l * 16384 * 768 + (lane & 31) * 24;
;   const unsigned char* V = P.V8 + (size_t)l * 16384 * 512 + lane * 8;
;   const float* SU = P.SU + l * 16384;
;   const float* SV = P.SV + l * 16384;
;   int nev0, nev1; float ngv0, ngv1; uint4 nxa, nxc;
;   {
;     const int t = blockIdx.x * 4 + w;
;     nev0 = P.EXP[(size_t)t * 128 + lane]; nev1 = P.EXP[(size_t)t * 128 + 64 + lane];
;     ngv0 = P.GATE[(size_t)t * 128 + lane]; ngv1 = P.GATE[(size_t)t * 128 + 64 + lane];
;     const bf16_t* xb = P.XB + (size_t)t * 1024 + lane * 16;
;     nxa = *(const uint4*)xb; nxc = *(const uint4*)(xb + 8);
;   }
;   for (int r4 = blockIdx.x; r4 < T_TOK / 4; r4 += gridDim.x) {
;     const int t = r4 * 4 + w;
;     f32x2 xf[8];
;     const int ev0 = nev0, ev1 = nev1; const float gv0 = ngv0, gv1 = ngv1;
.LBB0_14:
	v_readlane_b32 s4, v248, 27
	s_add_i32 s4, s4, 1
	v_readlane_b32 s2, v249, 37
	s_cmp_eq_u32 s4, s2
	v_writelane_b32 v248, s4, 27
	s_cselect_b64 s[4:5], -1, 0
	v_writelane_b32 v248, s4, 32
	s_mov_b64 s[0:1], -1
	s_nop 0
	v_writelane_b32 v248, s5, 33
	v_readlane_b32 s4, v249, 38
	v_readlane_b32 s5, v249, 39
	s_and_b64 vcc, exec, s[4:5]
	s_cbranch_vccz .LBB0_310
	v_readlane_b32 s0, v251, 58
	v_readlane_b32 s1, v251, 59
	s_load_dword s0, s[0:1], 0x0
	s_waitcnt lgkmcnt(0)
	v_writelane_b32 v248, s0, 34
	s_nop 1
	v_writelane_b32 v248, s1, 35
	v_readlane_b32 s0, v249, 40
	s_cmp_lt_i32 s0, 4
	s_mov_b64 s[0:1], -1
	s_cbranch_scc1 .LBB0_65
	v_readlane_b32 s0, v249, 40
	s_cmp_lt_i32 s0, 6
	s_mov_b64 s[0:1], -1
	s_cbranch_scc1 .LBB0_39
	v_readlane_b32 s0, v249, 40
	s_cmp_gt_i32 s0, 6
	s_cbranch_scc0 .LBB0_38
	v_readlane_b32 s0, v251, 60
	v_readlane_b32 s1, v251, 61
	v_mov_b32_e32 v0, v202
	v_mov_b32_e32 v1, v202
	s_andn2_b64 vcc, exec, s[0:1]
	s_cbranch_vccnz .LBB0_38
	v_ashrrev_i32_e32 v73, 6, v1
	v_and_b32_e32 v1, 31, v0
	v_readlane_b32 s0, v249, 41
	v_mul_u32_u24_e32 v176, 24, v1
	v_readlane_b32 s1, v249, 42
	v_and_b32_e32 v72, 63, v0
	v_readlane_b32 s4, v251, 2
	v_lshl_add_u64 v[74:75], s[0:1], 0, v[176:177]
	v_readlane_b32 s0, v249, 43
	v_lshlrev_b32_e32 v176, 3, v72
	v_readlane_b32 s1, v249, 44
	v_readlane_b32 s5, v251, 3
	v_readlane_b32 s6, v251, 4
	v_lshl_add_u64 v[76:77], s[0:1], 0, v[176:177]
	v_readlane_b32 s0, v251, 62
	v_lshlrev_b32_e32 v176, 5, v72
	v_readlane_b32 s7, v251, 5
	v_add_u32_e32 v2, s0, v73
	v_ashrrev_i32_e32 v3, 31, v2
	v_lshlrev_b64 v[4:5], 11, v[2:3]
	v_lshl_add_u64 v[4:5], s[28:29], 0, v[4:5]
	v_lshlrev_b64 v[2:3], 9, v[2:3]
	v_lshl_add_u64 v[4:5], v[4:5], 0, v[176:177]
	v_lshl_or_b32 v2, v72, 2, v2
	global_load_dwordx4 v[64:67], v[4:5], off offset:16
	global_load_dwordx4 v[68:71], v[4:5], off
	v_lshl_add_u64 v[4:5], s[4:5], 0, v[2:3]
	v_lshl_add_u64 v[2:3], s[6:7], 0, v[2:3]
	global_load_dword v93, v[4:5], off offset:256
	global_load_dword v91, v[4:5], off
	global_load_dword v188, v[2:3], off offset:256
	global_load_dword v179, v[2:3], off
	v_readlane_b32 s0, v249, 49
	v_readlane_b32 s4, v248, 32
	v_readlane_b32 s1, v249, 50
	v_readlane_b32 s5, v248, 33
	s_and_b64 s[38:39], s[0:1], s[4:5]
	v_readlane_b32 s0, v248, 1
	v_readlane_b32 s1, v248, 2
	s_and_b64 s[0:1], s[0:1], s[4:5]
	s_xor_b64 s[0:1], s[0:1], -1
	v_writelane_b32 v248, s0, 45
	v_lshl_add_u64 v[78:79], s[28:29], 0, v[176:177]
	v_lshlrev_b32_e32 v176, 6, v72
	v_writelane_b32 v248, s1, 46
	v_readlane_b32 s0, v249, 54
	v_readlane_b32 s1, v249, 55
	v_lshlrev_b32_e32 v0, 5, v0
	v_readlane_b32 s44, v252, 12
	v_lshl_add_u64 v[82:83], s[0:1], 0, v[176:177]
	v_readlane_b32 s0, v249, 56
	v_readlane_b32 s1, v249, 57
	v_lshlrev_b32_e32 v2, 4, v72
	v_and_b32_e32 v0, 0x3e0, v0
	v_readlane_b32 s58, v252, 26
	v_readlane_b32 s59, v252, 27
	v_lshl_add_u64 v[84:85], s[0:1], 0, v[176:177]
	v_readlane_b32 s0, v249, 5
	v_cmp_lt_u32_e64 s[40:41], 31, v72
	v_lshl_add_u64 v[80:81], s[58:59], 0, v[176:177]
	v_lshlrev_b32_e32 v86, 1, v0
	v_lshlrev_b32_e32 v176, 1, v2
	v_mov_b32_e32 v87, v177
	s_mov_b32 s2, s0
	s_movk_i32 s33, 0x300
	v_readlane_b32 s45, v252, 13
	v_readlane_b32 s46, v252, 14
	v_readlane_b32 s47, v252, 15
	v_readlane_b32 s48, v252, 16
	v_readlane_b32 s49, v252, 17
	v_readlane_b32 s50, v252, 18
	v_readlane_b32 s51, v252, 19
	v_readlane_b32 s52, v252, 20
	v_readlane_b32 s53, v252, 21
	v_readlane_b32 s54, v252, 22
	v_readlane_b32 s55, v252, 23
	v_readlane_b32 s56, v252, 24
	v_readlane_b32 s57, v252, 25
	v_readlane_b32 s1, v249, 6
	v_readlane_b32 s4, v249, 5
	s_bitcmp1_b32 s4, 8
	s_cbranch_scc0 .Lg_nostag
	s_sleep 127
	s_sleep 127
	s_sleep 127
	s_sleep 127
	s_sleep 127
.Lg_nostag:
	s_branch .LBB0_21
.LBB0_20:
	s_andn2_b64 vcc, exec, s[44:45]
	v_mov_b64_e32 v[70:71], v[62:63]
	v_mov_b64_e32 v[68:69], v[60:61]
	v_mov_b64_e32 v[66:67], v[58:59]
	v_mov_b64_e32 v[64:65], v[56:57]
	s_cbranch_vccz .LBB0_37
